# GEMM residual epilogue (h += acc, out = h + acc) replaced by a pipelined form: next chunk operand loads in flight while the current chunk is added and stored, counted vmcnt
# speedup vs baseline: 1.0074x; 1.0045x over previous
; __device__ __forceinline__ void epi8(const Desc& d, int pb, int row, int col, f32x4 v0, f32x4 v1) {
;     ...
;     } else {
;         float* hp = (float*)d.o0 + (size_t)row * DM + col;
;         const float* rp = (row < LREAL ? (const float*)d.o2 + (size_t)row * DM : (const float*)d.gate + (size_t)(row - LREAL) * DM) + col;
;         v0 += *(const f32x4*)rp; v1 += *(const f32x4*)(rp + 4);
;         if (d.epi == EPI_RESID) { *(f32x4*)hp = v0; *(f32x4*)(hp + 4) = v1; }
;         else if (row < LREAL) { float* op = (float*)d.o1 + (size_t)row * DM + col; *(f32x4*)op = v0; *(f32x4*)(op + 4) = v1; }
;     }
; }
; __device__ __forceinline__ void epilogue(const Desc& d, const f32x4 (&acc)[2][2][4][2], const Unit& u, int wr, int wc, int fr, int fq) {
;     const int row0 = u.pm * BM + wr * 64 + fr, col0 = u.pn * BM + wc * 32 + 8 * fq;
; #pragma unroll
;     for (int ai = 0; ai < 2; ++ai)
; #pragma unroll
;         for (int m = 0; m < 4; ++m) {
; #pragma unroll
;             for (int bj = 0; bj < 2; ++bj) epi8(d, u.pb, row0 + ai * HALF + m * 16, col0 + bj * HALF, acc[ai][bj][m][0], acc[ai][bj][m][1]);
;             asm volatile("" ::: "memory"); }
; }
.LBB0_313:
	v_lshl_add_u32 v158, s74, 8, v151
	s_cmp_gt_i32 s59, 20
	s_cselect_b64 s[40:41], -1, 0
	s_cmp_lg_u32 s59, 21
	v_ashrrev_i32_e32 v159, 31, v158
	v_mad_i64_i32 v[160:161], s[0:1], v158, s17, 0
	v_add_u32_e32 v128, 0xffffe000, v158
	v_mov_b32_e32 v129, v145
	v_lshl_or_b32 v144, s59, 8, v171
	s_cselect_b64 s[72:73], -1, 0
	v_lshlrev_b64 v[162:163], 11, v[158:159]
	v_cmp_gt_i32_e64 s[0:1], s19, v158
	v_lshlrev_b64 v[164:165], 13, v[128:129]
	s_cmp_gt_i32 s26, 4
	s_cbranch_scc0 .Lepi_generic
	v_ashrrev_i32_e32 v189, 31, v144
	v_mov_b32_e32 v188, v144
	v_lshl_add_u64 v[182:183], v[162:163], 2, s[86:87]
	v_lshl_add_u64 v[182:183], v[188:189], 2, v[182:183]
	s_cmp_lg_u64 s[64:65], 0
	s_cselect_b64 s[74:75], s[84:85], s[50:51]
	v_lshl_add_u64 v[184:185], v[162:163], 2, s[74:75]
	v_lshl_add_u64 v[184:185], v[188:189], 2, v[184:185]
	v_mov_b32_e32 v191, 0
	v_mov_b32_e32 v190, 0x0
	v_lshl_add_u64 v[186:187], v[190:191], 0, v[182:183]
	global_load_dwordx4 v[192:195], v[186:187], off
	global_load_dwordx4 v[196:199], v[186:187], off offset:16
	v_mov_b32_e32 v190, 0x0
	v_lshl_add_u64 v[186:187], v[190:191], 0, v[182:183]
	global_load_dwordx4 v[208:211], v[186:187], off offset:512
	global_load_dwordx4 v[212:215], v[186:187], off offset:528
	s_waitcnt vmcnt(2)
	v_pk_add_f32 v[192:193], v[124:125], v[192:193]
	v_pk_add_f32 v[194:195], v[126:127], v[194:195]
	v_pk_add_f32 v[196:197], v[120:121], v[196:197]
	v_pk_add_f32 v[198:199], v[122:123], v[198:199]
	v_mov_b32_e32 v190, 0x0
	v_lshl_add_u64 v[188:189], v[190:191], 0, v[184:185]
	global_store_dwordx4 v[188:189], v[192:195], off
	global_store_dwordx4 v[188:189], v[196:199], off offset:16
	v_mov_b32_e32 v190, 0x20000
	v_lshl_add_u64 v[186:187], v[190:191], 0, v[182:183]
	global_load_dwordx4 v[120:123], v[186:187], off
	global_load_dwordx4 v[124:127], v[186:187], off offset:16
	s_waitcnt vmcnt(2)
	v_pk_add_f32 v[208:209], v[116:117], v[208:209]
	v_pk_add_f32 v[210:211], v[118:119], v[210:211]
	v_pk_add_f32 v[212:213], v[112:113], v[212:213]
	v_pk_add_f32 v[214:215], v[114:115], v[214:215]
	v_mov_b32_e32 v190, 0x0
	v_lshl_add_u64 v[188:189], v[190:191], 0, v[184:185]
	global_store_dwordx4 v[188:189], v[208:211], off offset:512
	global_store_dwordx4 v[188:189], v[212:215], off offset:528
	v_mov_b32_e32 v190, 0x20000
	v_lshl_add_u64 v[186:187], v[190:191], 0, v[182:183]
	global_load_dwordx4 v[112:115], v[186:187], off offset:512
	global_load_dwordx4 v[116:119], v[186:187], off offset:528
	s_waitcnt vmcnt(2)
	v_pk_add_f32 v[120:121], v[108:109], v[120:121]
	v_pk_add_f32 v[122:123], v[110:111], v[122:123]
	v_pk_add_f32 v[124:125], v[104:105], v[124:125]
	v_pk_add_f32 v[126:127], v[106:107], v[126:127]
	v_mov_b32_e32 v190, 0x20000
	v_lshl_add_u64 v[188:189], v[190:191], 0, v[184:185]
	global_store_dwordx4 v[188:189], v[120:123], off
	global_store_dwordx4 v[188:189], v[124:127], off offset:16
	v_mov_b32_e32 v190, 0x40000
	v_lshl_add_u64 v[186:187], v[190:191], 0, v[182:183]
	global_load_dwordx4 v[104:107], v[186:187], off
	global_load_dwordx4 v[108:111], v[186:187], off offset:16
	s_waitcnt vmcnt(2)
	v_pk_add_f32 v[112:113], v[100:101], v[112:113]
	v_pk_add_f32 v[114:115], v[102:103], v[114:115]
	v_pk_add_f32 v[116:117], v[96:97], v[116:117]
	v_pk_add_f32 v[118:119], v[98:99], v[118:119]
	v_mov_b32_e32 v190, 0x20000
	v_lshl_add_u64 v[188:189], v[190:191], 0, v[184:185]
	global_store_dwordx4 v[188:189], v[112:115], off offset:512
	global_store_dwordx4 v[188:189], v[116:119], off offset:528
	v_mov_b32_e32 v190, 0x40000
	v_lshl_add_u64 v[186:187], v[190:191], 0, v[182:183]
	global_load_dwordx4 v[96:99], v[186:187], off offset:512
	global_load_dwordx4 v[100:103], v[186:187], off offset:528
	s_waitcnt vmcnt(2)
	v_pk_add_f32 v[104:105], v[92:93], v[104:105]
	v_pk_add_f32 v[106:107], v[94:95], v[106:107]
	v_pk_add_f32 v[108:109], v[88:89], v[108:109]
	v_pk_add_f32 v[110:111], v[90:91], v[110:111]
	v_mov_b32_e32 v190, 0x40000
	v_lshl_add_u64 v[188:189], v[190:191], 0, v[184:185]
	global_store_dwordx4 v[188:189], v[104:107], off
	global_store_dwordx4 v[188:189], v[108:111], off offset:16
	v_mov_b32_e32 v190, 0x60000
	v_lshl_add_u64 v[186:187], v[190:191], 0, v[182:183]
	global_load_dwordx4 v[88:91], v[186:187], off
	global_load_dwordx4 v[92:95], v[186:187], off offset:16
	s_waitcnt vmcnt(2)
	v_pk_add_f32 v[96:97], v[84:85], v[96:97]
	v_pk_add_f32 v[98:99], v[86:87], v[98:99]
	v_pk_add_f32 v[100:101], v[80:81], v[100:101]
	v_pk_add_f32 v[102:103], v[82:83], v[102:103]
	v_mov_b32_e32 v190, 0x40000
	v_lshl_add_u64 v[188:189], v[190:191], 0, v[184:185]
	global_store_dwordx4 v[188:189], v[96:99], off offset:512
	global_store_dwordx4 v[188:189], v[100:103], off offset:528
	v_mov_b32_e32 v190, 0x60000
	v_lshl_add_u64 v[186:187], v[190:191], 0, v[182:183]
	global_load_dwordx4 v[80:83], v[186:187], off offset:512
	global_load_dwordx4 v[84:87], v[186:187], off offset:528
	s_waitcnt vmcnt(2)
	v_pk_add_f32 v[88:89], v[76:77], v[88:89]
	v_pk_add_f32 v[90:91], v[78:79], v[90:91]
	v_pk_add_f32 v[92:93], v[72:73], v[92:93]
	v_pk_add_f32 v[94:95], v[74:75], v[94:95]
	v_mov_b32_e32 v190, 0x60000
	v_lshl_add_u64 v[188:189], v[190:191], 0, v[184:185]
	global_store_dwordx4 v[188:189], v[88:91], off
	global_store_dwordx4 v[188:189], v[92:95], off offset:16
	v_mov_b32_e32 v190, 0x100000
	v_lshl_add_u64 v[186:187], v[190:191], 0, v[182:183]
	global_load_dwordx4 v[72:75], v[186:187], off
	global_load_dwordx4 v[76:79], v[186:187], off offset:16
	s_waitcnt vmcnt(2)
; __device__ __forceinline__ void epi8(const Desc& d, int pb, int row, int col, f32x4 v0, f32x4 v1) {
;     ...
;     } else {
;         float* hp = (float*)d.o0 + (size_t)row * DM + col;
;         const float* rp = (row < LREAL ? (const float*)d.o2 + (size_t)row * DM : (const float*)d.gate + (size_t)(row - LREAL) * DM) + col;
;         v0 += *(const f32x4*)rp; v1 += *(const f32x4*)(rp + 4);
;         if (d.epi == EPI_RESID) { *(f32x4*)hp = v0; *(f32x4*)(hp + 4) = v1; }
;         else if (row < LREAL) { float* op = (float*)d.o1 + (size_t)row * DM + col; *(f32x4*)op = v0; *(f32x4*)(op + 4) = v1; }
;     }
; }
; __device__ __forceinline__ void epilogue(const Desc& d, const f32x4 (&acc)[2][2][4][2], const Unit& u, int wr, int wc, int fr, int fq) {
;     const int row0 = u.pm * BM + wr * 64 + fr, col0 = u.pn * BM + wc * 32 + 8 * fq;
; #pragma unroll
;     for (int ai = 0; ai < 2; ++ai)
; #pragma unroll
;         for (int m = 0; m < 4; ++m) {
; #pragma unroll
;             for (int bj = 0; bj < 2; ++bj) epi8(d, u.pb, row0 + ai * HALF + m * 16, col0 + bj * HALF, acc[ai][bj][m][0], acc[ai][bj][m][1]);
;             asm volatile("" ::: "memory"); }
; }
	v_pk_add_f32 v[80:81], v[68:69], v[80:81]
	v_pk_add_f32 v[82:83], v[70:71], v[82:83]
	v_pk_add_f32 v[84:85], v[64:65], v[84:85]
	v_pk_add_f32 v[86:87], v[66:67], v[86:87]
	v_mov_b32_e32 v190, 0x60000
	v_lshl_add_u64 v[188:189], v[190:191], 0, v[184:185]
	global_store_dwordx4 v[188:189], v[80:83], off offset:512
	global_store_dwordx4 v[188:189], v[84:87], off offset:528
	v_mov_b32_e32 v190, 0x100000
	v_lshl_add_u64 v[186:187], v[190:191], 0, v[182:183]
	global_load_dwordx4 v[64:67], v[186:187], off offset:512
	global_load_dwordx4 v[68:71], v[186:187], off offset:528
	s_waitcnt vmcnt(2)
	v_pk_add_f32 v[72:73], v[60:61], v[72:73]
	v_pk_add_f32 v[74:75], v[62:63], v[74:75]
	v_pk_add_f32 v[76:77], v[56:57], v[76:77]
	v_pk_add_f32 v[78:79], v[58:59], v[78:79]
	v_mov_b32_e32 v190, 0x100000
	v_lshl_add_u64 v[188:189], v[190:191], 0, v[184:185]
	global_store_dwordx4 v[188:189], v[72:75], off
	global_store_dwordx4 v[188:189], v[76:79], off offset:16
	v_mov_b32_e32 v190, 0x120000
	v_lshl_add_u64 v[186:187], v[190:191], 0, v[182:183]
	global_load_dwordx4 v[56:59], v[186:187], off
	global_load_dwordx4 v[60:63], v[186:187], off offset:16
	s_waitcnt vmcnt(2)
	v_pk_add_f32 v[64:65], v[52:53], v[64:65]
	v_pk_add_f32 v[66:67], v[54:55], v[66:67]
	v_pk_add_f32 v[68:69], v[48:49], v[68:69]
	v_pk_add_f32 v[70:71], v[50:51], v[70:71]
	v_mov_b32_e32 v190, 0x100000
	v_lshl_add_u64 v[188:189], v[190:191], 0, v[184:185]
	global_store_dwordx4 v[188:189], v[64:67], off offset:512
	global_store_dwordx4 v[188:189], v[68:71], off offset:528
	v_mov_b32_e32 v190, 0x120000
	v_lshl_add_u64 v[186:187], v[190:191], 0, v[182:183]
	global_load_dwordx4 v[48:51], v[186:187], off offset:512
	global_load_dwordx4 v[52:55], v[186:187], off offset:528
	s_waitcnt vmcnt(2)
	v_pk_add_f32 v[56:57], v[44:45], v[56:57]
	v_pk_add_f32 v[58:59], v[46:47], v[58:59]
	v_pk_add_f32 v[60:61], v[40:41], v[60:61]
	v_pk_add_f32 v[62:63], v[42:43], v[62:63]
	v_mov_b32_e32 v190, 0x120000
	v_lshl_add_u64 v[188:189], v[190:191], 0, v[184:185]
	global_store_dwordx4 v[188:189], v[56:59], off
	global_store_dwordx4 v[188:189], v[60:63], off offset:16
	v_mov_b32_e32 v190, 0x140000
	v_lshl_add_u64 v[186:187], v[190:191], 0, v[182:183]
	global_load_dwordx4 v[40:43], v[186:187], off
	global_load_dwordx4 v[44:47], v[186:187], off offset:16
	s_waitcnt vmcnt(2)
	v_pk_add_f32 v[48:49], v[36:37], v[48:49]
	v_pk_add_f32 v[50:51], v[38:39], v[50:51]
	v_pk_add_f32 v[52:53], v[32:33], v[52:53]
	v_pk_add_f32 v[54:55], v[34:35], v[54:55]
	v_mov_b32_e32 v190, 0x120000
	v_lshl_add_u64 v[188:189], v[190:191], 0, v[184:185]
	global_store_dwordx4 v[188:189], v[48:51], off offset:512
	global_store_dwordx4 v[188:189], v[52:55], off offset:528
	v_mov_b32_e32 v190, 0x140000
	v_lshl_add_u64 v[186:187], v[190:191], 0, v[182:183]
	global_load_dwordx4 v[32:35], v[186:187], off offset:512
	global_load_dwordx4 v[36:39], v[186:187], off offset:528
	s_waitcnt vmcnt(2)
	v_pk_add_f32 v[40:41], v[28:29], v[40:41]
	v_pk_add_f32 v[42:43], v[30:31], v[42:43]
	v_pk_add_f32 v[44:45], v[24:25], v[44:45]
	v_pk_add_f32 v[46:47], v[26:27], v[46:47]
	v_mov_b32_e32 v190, 0x140000
	v_lshl_add_u64 v[188:189], v[190:191], 0, v[184:185]
	global_store_dwordx4 v[188:189], v[40:43], off
	global_store_dwordx4 v[188:189], v[44:47], off offset:16
	v_mov_b32_e32 v190, 0x160000
	v_lshl_add_u64 v[186:187], v[190:191], 0, v[182:183]
	global_load_dwordx4 v[24:27], v[186:187], off
	global_load_dwordx4 v[28:31], v[186:187], off offset:16
	s_waitcnt vmcnt(2)
	v_pk_add_f32 v[32:33], v[20:21], v[32:33]
	v_pk_add_f32 v[34:35], v[22:23], v[34:35]
	v_pk_add_f32 v[36:37], v[16:17], v[36:37]
	v_pk_add_f32 v[38:39], v[18:19], v[38:39]
	v_mov_b32_e32 v190, 0x140000
	v_lshl_add_u64 v[188:189], v[190:191], 0, v[184:185]
	global_store_dwordx4 v[188:189], v[32:35], off offset:512
	global_store_dwordx4 v[188:189], v[36:39], off offset:528
	v_mov_b32_e32 v190, 0x160000
	v_lshl_add_u64 v[186:187], v[190:191], 0, v[182:183]
	global_load_dwordx4 v[16:19], v[186:187], off offset:512
	global_load_dwordx4 v[20:23], v[186:187], off offset:528
	s_waitcnt vmcnt(2)
	v_pk_add_f32 v[24:25], v[12:13], v[24:25]
	v_pk_add_f32 v[26:27], v[14:15], v[26:27]
	v_pk_add_f32 v[28:29], v[8:9], v[28:29]
	v_pk_add_f32 v[30:31], v[10:11], v[30:31]
	v_mov_b32_e32 v190, 0x160000
	v_lshl_add_u64 v[188:189], v[190:191], 0, v[184:185]
	global_store_dwordx4 v[188:189], v[24:27], off
	global_store_dwordx4 v[188:189], v[28:31], off offset:16
	s_waitcnt vmcnt(0)
	v_pk_add_f32 v[16:17], v[0:1], v[16:17]
	v_pk_add_f32 v[18:19], v[2:3], v[18:19]
	v_pk_add_f32 v[20:21], v[4:5], v[20:21]
	v_pk_add_f32 v[22:23], v[6:7], v[22:23]
	v_mov_b32_e32 v190, 0x160000
	v_lshl_add_u64 v[188:189], v[190:191], 0, v[184:185]
	global_store_dwordx4 v[188:189], v[16:19], off offset:512
	global_store_dwordx4 v[188:189], v[20:23], off offset:528
	s_branch .LBB0_777
.Lepi_generic:
	s_cmp_lt_i32 s26, 1
	s_mov_b64 s[74:75], -1
	s_cbranch_scc0 .LBB0_317
	v_lshlrev_b64 v[130:131], 9, v[158:159]
	s_andn2_b64 vcc, exec, s[74:75]
	v_mad_i64_i32 v[128:129], s[42:43], v158, s27, 0
	s_cbranch_vccz .LBB0_335
